# MoBA hoisted lookup: cnt and list byte read in one LDS round trip; per-step item count cached in a spill lane for the exists checks
# baseline (speedup 1.0000x reference)
; #define MB_LOAD(nn) do { _Pragma("unroll") for (int i = 0; i < 4; ++i) { const int cidx = tid + 512 * i, row = cidx >> 3, ch = cidx & 7; \
;         const bf16* src = Zb + (size_t)((nn) * 256 + row) * ZC + h * 64 + ch * 8; kreg[i] = *(const v4u*)(src + KC); vreg[i] = *(const v4u*)(src + VC); } } while (0)
; #define MB_STORE() do { _Pragma("unroll") for (int i = 0; i < 4; ++i) { const int cidx = tid + 512 * i, row = cidx >> 3, ch = cidx & 7; \
;         *(LAS v4u*)(lds + MB_K + row * 144 + ch * 16) = kreg[i]; *(LAS v4u*)(lds + MB_V + row * 144 + ch * 16) = vreg[i]; } } while (0)
; #define MB_QID(st, k, qid, valid) do { if ((st) == 0) { const int it_ = (k) ? 15 - C.wave : C.wave; qid = 16 * it_ + i16; valid = true; } \
;         else { const int pos_ = 16 * (C.wave + 8 * (k)) + i16; valid = pos_ < cnt[(st) - 1]; qid = lists[((st) - 1) * 256 + (valid ? pos_ : 0)]; } } while (0)
; #define MB_QLOAD(qid, d0, d1) do { const bf16* qp_ = Zb + (size_t)(qb * 256 + (qid)) * ZC + QC + h * 64 + 8 * (lane >> 4); d0 = *(const bf16x8*)qp_; d1 = *(const bf16x8*)(qp_ + 32); } while (0)
; __device__ __forceinline__ void moba_unit(const Ctx& C, int unit, const float* KM) {
;     ...
;     MB_LOAD(qb);
;     __syncthreads();
;     for (int step = 0; step <= qb; ++step) {
;         __syncthreads();
;         MB_STORE();
;         __syncthreads();
;         if (step < qb) MB_LOAD(step);
; #pragma unroll 1
;         for (int k = 0; MB_EXISTS(step, k); ++k) {
;             int cqid; bool cvalid; bf16x8 cq0, cq1;
;             MB_QID(step, k, cqid, cvalid); MB_QLOAD(cqid, cq0, cq1);
.LBB0_487:
	s_cmp_eq_u32 s52, 0
	s_cbranch_scc1 .Lqp_step0
	s_lshl_b32 s22, s52, 2
	v_mov_b32_e32 v33, s22
	ds_read_b32 v33, v33 offset:60
	s_add_i32 s22, s52, -1
	s_lshl_b32 s22, s22, 8
	v_add_u32_e32 v34, s22, v217
	ds_read_u8 v221, v34 offset:3072
	s_waitcnt lgkmcnt(1)
	v_cmp_lt_i32_e64 s[100:101], v217, v33
	v_readfirstlane_b32 s22, v33
	s_add_i32 s22, s22, 15
	s_ashr_i32 s22, s22, 4
	v_writelane_b32 v247, s22, 40
	s_waitcnt lgkmcnt(0)
	v_add_u32_e32 v34, s75, v221
	v_mov_b64_e32 v[32:33], s[66:67]
	v_mad_i64_i32 v[32:33], s[22:23], v34, s33, v[32:33]
	v_lshl_add_u64 v[32:33], v[32:33], 0, s[36:37]
	v_lshl_add_u64 v[32:33], v[32:33], 0, v[192:193]
	v_lshl_add_u64 v[34:35], v[32:33], 0, s[88:89]
	v_add_co_u32_e32 v32, vcc, 0x1000, v32
	s_nop 1
	v_addc_co_u32_e32 v33, vcc, 0, v33, vcc
	global_load_dwordx4 v[96:99], v[32:33], off offset:2560
	global_load_dwordx4 v[100:103], v[34:35], off offset:64
	v_add_u32_e32 v32, v206, v213
	s_barrier
	s_waitcnt vmcnt(9)
	ds_write_b128 v32, v[0:3]
	v_add_u32_e32 v32, v207, v213
	s_waitcnt vmcnt(8)
	ds_write_b128 v32, v[4:7]
	v_add_u32_e32 v32, v206, v214
	s_waitcnt vmcnt(7)
	ds_write_b128 v32, v[8:11]
	v_add_u32_e32 v32, v207, v214
	s_waitcnt vmcnt(6)
	ds_write_b128 v32, v[12:15]
	v_add_u32_e32 v32, v206, v215
	s_waitcnt vmcnt(5)
	ds_write_b128 v32, v[16:19]
	v_add_u32_e32 v32, v207, v215
	s_waitcnt vmcnt(4)
	ds_write_b128 v32, v[20:23]
	v_add_u32_e32 v32, v206, v216
	s_waitcnt vmcnt(3)
	ds_write_b128 v32, v[24:27]
	v_add_u32_e32 v32, v207, v216
	s_cmp_ge_i32 s52, s70
	s_waitcnt vmcnt(2)
	ds_write_b128 v32, v[28:31]
	s_waitcnt lgkmcnt(0)
	s_barrier
	s_branch .LBB0_489

; #define MB_LOAD(nn) do { _Pragma("unroll") for (int i = 0; i < 4; ++i) { const int cidx = tid + 512 * i, row = cidx >> 3, ch = cidx & 7; \
;         const bf16* src = Zb + (size_t)((nn) * 256 + row) * ZC + h * 64 + ch * 8; kreg[i] = *(const v4u*)(src + KC); vreg[i] = *(const v4u*)(src + VC); } } while (0)
; #define MB_STORE() do { _Pragma("unroll") for (int i = 0; i < 4; ++i) { const int cidx = tid + 512 * i, row = cidx >> 3, ch = cidx & 7; \
;         *(LAS v4u*)(lds + MB_K + row * 144 + ch * 16) = kreg[i]; *(LAS v4u*)(lds + MB_V + row * 144 + ch * 16) = vreg[i]; } } while (0)
; __device__ __forceinline__ void moba_unit(const Ctx& C, int unit, const float* KM) {
;     ...
;     MB_LOAD(qb);
;     __syncthreads();
;     for (int step = 0; step <= qb; ++step) {
;         __syncthreads();
;         MB_STORE();
;         __syncthreads();
;         if (step < qb) MB_LOAD(step);
; #pragma unroll 1
;         for (int k = 0; MB_EXISTS(step, k); ++k) {
.LBB0_491:
	s_mov_b64 s[42:43], -1
	s_and_b64 vcc, exec, s[48:49]
	s_cbranch_vccz .LBB0_494
	v_readlane_b32 s22, v247, 40
	s_nop 1
	s_cmp_lt_i32 s56, s22
	s_cselect_b64 s[40:41], -1, 0
	s_cbranch_execz .LBB0_495
